# group barrier 2 split-phase: arrive after the P2 state scan, wait only before the retention blocks (attention blocks run in between)
# speedup vs baseline: 1.0030x; 1.0030x over previous
; __device__ __forceinline__ unsigned xb_ld(unsigned* p)              { return __hip_atomic_load(p, __ATOMIC_RELAXED, __HIP_MEMORY_SCOPE_AGENT); }
; __device__ __forceinline__ unsigned xb_add(unsigned* p, unsigned v) { return __hip_atomic_fetch_add(p, v, __ATOMIC_RELAXED, __HIP_MEMORY_SCOPE_AGENT); }
; #define XB_SPIN(cond, bar) do { unsigned _sp = 0; while (cond) { __builtin_amdgcn_s_sleep(1); \
;     if ((++_sp & 255u) == 0u) { if (xb_ld(&(bar)[XB_TMO])) break; if (_sp > XB_SPIN_CAP) { atomicAdd(&(bar)[XB_TMO], 1u); break; } } } } while (0)
; __device__ __forceinline__ void xcd_barrier(const XcdBarrier& b) {
;     asm volatile("s_waitcnt vmcnt(0)" ::: "memory");
;     __syncthreads();
;     if (threadIdx.x == 0) {
;         unsigned* bar = b.bar;
;         __builtin_amdgcn_s_waitcnt(0);
;         unsigned nloc = b.st[0], nx = b.st[1];
;         if (nloc == 0u) { xcd_barrier_complete(bar, b.x, nloc, nx); b.st[0] = nloc; b.st[1] = nx; }
;         const unsigned old = xb_add(&bar[XB_XSUB(b.x)], 1u);
;         const unsigned gen = old / nloc;
;         if (old + 1u == (gen + 1u) * nloc) {
;             __builtin_amdgcn_fence(__ATOMIC_RELEASE, "agent");
;             asm volatile("s_waitcnt vmcnt(0)" ::: "memory");
;             const unsigned og = xb_add(&bar[XB_TOP], 1u);
;             const unsigned tg = og / nx;
;             if (og + 1u == (tg + 1u) * nx) xb_add(&bar[XB_TOPGEN], 1u);
;             else XB_SPIN(xb_ld(&bar[XB_TOPGEN]) == tg, bar);
;             __builtin_amdgcn_fence(__ATOMIC_ACQUIRE, "agent");
;             xb_add(&bar[XB_XGEN(b.x)], 1u);
;             asm volatile("s_waitcnt vmcnt(0)" ::: "memory");
;         } else {
;             XB_SPIN(xb_ld(&bar[XB_XGEN(b.x)]) == gen, bar);
;             __builtin_amdgcn_fence(__ATOMIC_ACQUIRE, "agent");
;             asm volatile("s_waitcnt vmcnt(0)" ::: "memory");
;         }
;     }
;     __syncthreads();
.LBB0_251:
	s_cmp_gt_i32 s71, 3
	s_cselect_b64 s[0:1], -1, 0
	s_and_b64 s[6:7], s[6:7], s[0:1]
	s_andn2_b64 vcc, exec, s[6:7]
	s_cbranch_vccnz .LBB0_305
	s_waitcnt vmcnt(0)
	s_waitcnt vmcnt(0)
	s_barrier
	s_and_saveexec_b64 s[6:7], s[96:97]
	s_cbranch_execz .LBB0_304
	s_cmp_eq_u32 s99, 1
	s_cbranch_scc0 .Lgb2_global
	s_and_b32 s100, s2, 7
	s_lshl_b32 s100, s100, 8
	s_add_u32 s100, s100, 0x2d800
	v_mov_b32_e32 v254, s100
	v_mov_b32_e32 v255, 1
	global_atomic_add v254, v255, s[76:77]
	s_branch .LBB0_304

; #define GRID_BAR(k) do { if (IN(k) && IN((k) + 1)) xcd_barrier(bar); } while (0)
; __global__ void __launch_bounds__(NWAVES * 64, 2) hybrid_fwd(Args args) {
;     ...
;     GRID_BAR(2);
;     if (IN(3)) {
;         for (int it = vcu; it < 256; it += G) { const int bh = it >> 2, s = it & 3;
; #pragma unroll 1
;             for (int ps = 0; ps < 2; ++ps) fa::attn_block(PROJ, MIXED, bh >> 3, bh & 7, ps ? s : 7 - s, (char*)lds); }
;         for (int it = vcu; it < 256; it += G) { const int bh = it >> 3, s = it & 7;
; #pragma unroll 1
;             for (int ps = 0; ps < 2; ++ps) fa::ret_block(PROJ, HB, MIXED, bh >> 2, bh & 3, ps ? s : 15 - s, (char*)lds); }
.LBB0_471:
	s_cmp_eq_u32 s99, 1
	s_cbranch_scc0 .Lgb2w_skip
	v_readfirstlane_b32 s100, v185
	s_cmp_lg_u32 s100, 0
	s_cbranch_scc1 .Lgb2w_bar
	s_and_b32 s100, s2, 7
	s_lshl_b32 s100, s100, 8
	s_add_u32 s100, s100, 0x2d800
	v_mov_b32_e32 v254, s100
	s_mov_b32 s100, 0

; __device__ __forceinline__ int crow(int r, int hi) { return (r & 3) + 8 * (r >> 2) + 4 * hi; }
; __device__ __forceinline__ unsigned cvtpk(float lo, float hi) { unsigned r; asm volatile("v_cvt_pk_bf16_f32 %0, %1, %2" : "=v"(r) : "v"(lo), "v"(hi)); return r; }
; __device__ __forceinline__ float bf2f(bf16_t v) { return __uint_as_float(((unsigned)v) << 16); }
; __device__ __forceinline__ void ret_block(const bf16_t* __restrict__ proj, const bf16_t* __restrict__ state, bf16_t* __restrict__ mixed, int b, int h, int qb, char* lds) {
;     ...
;         for (int d0 = 0; d0 < 4; ++d0) graw[r][d0] = Gp[(size_t)crow(r, hi) * LDQ + d0 * 32 + r32];
;     float ssr[16];
; #pragma unroll
;     for (int r = 0; r < 16; ++r) { float s = 0.f;
; #pragma unroll
;         for (int d0 = 0; d0 < 4; ++d0) s += o[d0][r] * o[d0][r];
;         s += __shfl_xor(s, 1); s += __shfl_xor(s, 2); s += __shfl_xor(s, 4); s += __shfl_xor(s, 8); s += __shfl_xor(s, 16);
;         ssr[r] = s; }
;     if (r32 == 0) {
; #pragma unroll
;         for (int r = 0; r < 16; ++r) ssx[e * 128 + wq * 32 + crow(r, hi)] = ssr[r]; }
;     __syncthreads();
; #pragma unroll
;     for (int r = 0; r < 16; ++r) { const int orow = crow(r, hi); const float tot = ssx[wq * 32 + orow] + ssx[128 + wq * 32 + orow];
;         const float rs = __builtin_amdgcn_rsqf(tot * (1.0f / 256.0f) + 1e-6f);
; #pragma unroll
;         for (int d0 = 0; d0 < 4; ++d0) { const float g = bf2f(graw[r][d0]);
;             const float v = o[d0][r] * rs * g * __builtin_amdgcn_rcpf(1.0f + __builtin_amdgcn_exp2f(-LOG2E * g)); const float vn = __shfl_xor(v, 1);
;             if ((r32 & 1) == 0) *(unsigned*)(Op + (size_t)orow * LDO + d0 * 32 + r32) = cvtpk(v, vn); } }
.Lgb2w_acq:
	buffer_inv sc1
	s_waitcnt vmcnt(0)
.Lgb2w_bar:
	s_barrier
.Lgb2w_skip:
	v_xor_b32_e32 v0, 2, v186
	v_cmp_lt_i32_e32 vcc, v0, v6
	v_readlane_b32 s70, v244, 10
	v_readlane_b32 s96, v244, 37
	v_cndmask_b32_e32 v0, v186, v0, vcc
	v_lshlrev_b32_e32 v157, 2, v0
	v_xor_b32_e32 v0, 4, v186
	v_cmp_lt_i32_e32 vcc, v0, v6
	v_readlane_b32 s72, v244, 35
	v_readlane_b32 s78, v244, 31
	v_cndmask_b32_e32 v0, v186, v0, vcc
	v_lshlrev_b32_e32 v158, 2, v0
	v_xor_b32_e32 v0, 8, v186
	v_cmp_lt_i32_e32 vcc, v0, v6
	s_movk_i32 s33, 0x3800
	v_mov_b32_e32 v153, 0
	v_cndmask_b32_e32 v0, v186, v0, vcc
	v_lshlrev_b32_e32 v159, 2, v0
	v_xor_b32_e32 v0, 16, v186
	v_cmp_lt_i32_e32 vcc, v0, v6
	s_add_i32 s40, 0, 0x10000
	s_add_i32 s41, 0, 0x14000
	v_cndmask_b32_e32 v0, v186, v0, vcc
	v_lshlrev_b32_e32 v160, 2, v0
	s_movk_i32 s42, 0x3000
	v_mov_b32_e32 v161, 0x358637bd
	v_mov_b32_e32 v162, 0x7000
	v_mov_b32_e32 v163, 0x18800
	v_mov_b32_e32 v164, 0x1c000
	v_mov_b32_e32 v165, 0x1f800
	v_mov_b32_e32 v166, 0x23000
	v_mov_b32_e32 v167, 0x34800
	v_mov_b32_e32 v168, 0x38000
	v_mov_b32_e32 v169, 0x3b800
	v_mov_b32_e32 v170, 0x3f000
	v_mov_b32_e32 v171, 0x50800
	v_mov_b32_e32 v172, 0x54000
	v_mov_b32_e32 v173, 0x57800
	v_mov_b32_e32 v174, 0x5b000
	v_mov_b32_e32 v175, 0x2000
	v_mov_b32_e32 v176, 0x3000
	v_mov_b32_e32 v177, 0x8000
	v_mov_b32_e32 v178, 0x9000
	v_mov_b32_e32 v179, 0xa000
	v_mov_b32_e32 v180, 0xb000
	v_mov_b32_e32 v181, 0x10000
	v_mov_b32_e32 v182, 0x11000
	v_mov_b32_e32 v183, 0x12000
	v_mov_b32_e32 v186, 0x13000
	v_mov_b32_e32 v187, 0x18000
	v_mov_b32_e32 v188, 0x19000
	v_mov_b32_e32 v189, 0x1a000
	v_mov_b32_e32 v190, 0x1b000
	v_readlane_b32 s71, v244, 11
	v_readlane_b32 s74, v244, 28
	v_readlane_b32 s97, v244, 38
	v_readlane_b32 s73, v244, 36
	v_readlane_b32 s79, v244, 32
	s_branch .LBB0_473
